# PP->G2 grid barrier replaced by a 4-block same-XCD counter rendezvous (PP rows remapped to the block's own G2 row-tile quarter); grid barrier kept when the XCC-major map is inactive
# speedup vs baseline: 1.0057x; 1.0057x over previous
; DI unsigned xb_ld(unsigned* p)              { return __hip_atomic_load(p, __ATOMIC_RELAXED, __HIP_MEMORY_SCOPE_AGENT); }
; __global__ void __launch_bounds__(NT, 2) fwd_megakernel(Params p) {
;     ...
;     int vb = bid, vc = bid;
;     if (G == 256 && lo == 0 && hi > 1) {
;         bool ok = true;
;         for (int j = 0; j < 8; ++j) ok = ok && (xb_ld(&slotw[64 * j]) == 32u);
;         if (ok) { const int xc = (int)xst[2], sl = (int)xst[3]; vb = xc * 32 + sl; vc = sl * 8 + xc; }
;     }
;     vb = __builtin_amdgcn_readfirstlane(vb); vc = __builtin_amdgcn_readfirstlane(vc);
.LBB0_108:
	v_writelane_b32 v250, 0, 60
	v_writelane_b32 v250, 4, 61
	s_cmp_gt_i32 s33, 1
	s_cselect_b64 s[0:1], -1, 0
	s_and_b64 s[0:1], s[6:7], s[0:1]
	s_andn2_b64 vcc, exec, s[0:1]
	v_mov_b32_e32 v2, s53
	v_mov_b32_e32 v1, s53
	s_cbranch_vccnz .LBB0_118
	v_mov_b32_e32 v1, 0
	global_load_dword v1, v1, s[2:3] sc1
	v_mov_b32_e32 v2, s53
	s_waitcnt vmcnt(0)
	v_cmp_ne_u32_e32 vcc, 32, v1
	v_mov_b32_e32 v1, s53
	s_cbranch_vccnz .LBB0_118
	v_mov_b32_e32 v3, 0x3000
	global_load_dword v1, v3, s[92:93] offset:1792 sc1
	v_mov_b32_e32 v2, s53
	s_waitcnt vmcnt(0)
	v_cmp_ne_u32_e32 vcc, 32, v1
	v_mov_b32_e32 v1, s53
	s_cbranch_vccnz .LBB0_118
	global_load_dword v1, v3, s[92:93] offset:2048 sc1
	v_mov_b32_e32 v2, s53
	s_waitcnt vmcnt(0)
	v_cmp_ne_u32_e32 vcc, 32, v1
	v_mov_b32_e32 v1, s53
	s_cbranch_vccnz .LBB0_118
	v_mov_b32_e32 v3, 0x3000
	global_load_dword v1, v3, s[92:93] offset:2304 sc1
	v_mov_b32_e32 v2, s53
	s_waitcnt vmcnt(0)
	v_cmp_ne_u32_e32 vcc, 32, v1
	v_mov_b32_e32 v1, s53
	s_cbranch_vccnz .LBB0_118
	global_load_dword v1, v3, s[92:93] offset:2560 sc1
	v_mov_b32_e32 v2, s53
	s_waitcnt vmcnt(0)
	v_cmp_ne_u32_e32 vcc, 32, v1
	v_mov_b32_e32 v1, s53
	s_cbranch_vccnz .LBB0_118
	v_mov_b32_e32 v3, 0x3000
	global_load_dword v1, v3, s[92:93] offset:2816 sc1
	v_mov_b32_e32 v2, s53
	s_waitcnt vmcnt(0)
	v_cmp_ne_u32_e32 vcc, 32, v1
	v_mov_b32_e32 v1, s53
	s_cbranch_vccnz .LBB0_118
	global_load_dword v1, v3, s[92:93] offset:3072 sc1
	v_mov_b32_e32 v2, s53
	s_waitcnt vmcnt(0)
	v_cmp_ne_u32_e32 vcc, 32, v1
	v_mov_b32_e32 v1, s53
	s_cbranch_vccnz .LBB0_118
	v_mov_b32_e32 v1, 0x3000
	global_load_dword v1, v1, s[92:93] offset:3328 sc1
	v_mov_b32_e32 v2, s53
	s_waitcnt vmcnt(0)
	v_cmp_ne_u32_e32 vcc, 32, v1
	v_mov_b32_e32 v1, s53
	s_cbranch_vccnz .LBB0_118
	v_writelane_b32 v250, 1, 60
	s_add_i32 s0, 0, 0x23ff8
	v_mov_b32_e32 v1, s0
	s_add_i32 s0, 0, 0x23ffc
	ds_read_b32 v2, v1
	v_mov_b32_e32 v1, s0
	ds_read_b32 v1, v1
	s_waitcnt lgkmcnt(0)
	v_lshlrev_b32_e32 v3, 5, v2
	v_lshlrev_b32_e32 v4, 3, v1
	v_add_u32_e32 v1, v3, v1
	v_add_u32_e32 v2, v4, v2

; DI void phase_post(const Params& p, int l, int G, int bid) {
;     ...
;     if (bid * 8 + wave < MSEG * 2) PP_LOAD(bid * 8 + wave);
;     for (int it = bid * 8 + wave; it < MSEG * 2; it += G * 8) {
;         const int lrow = it >> 1, grp = it & 1;
;         bf16_t* cp = P + (size_t)lrow * NPC + grp * 1024 + 16 * lane;
;         const u32x4 c0 = nc0, c1 = nc1, z0 = nz0, z1 = nz1, o0 = no0, o1 = no1;
;         const float inv = (grp == 0) ? 1.0f / ndn : 1.f;
;         if (it + G * 8 < MSEG * 2) PP_LOAD(it + G * 8);
.LBB0_691:
.LBB0_692:
	v_readlane_b32 s0, v252, 4
	v_readlane_b32 s1, v252, 5
	s_cmp_ge_i32 s88, s0
	s_cselect_b64 s[0:1], -1, 0
	s_cmp_lt_i32 s88, s33
	s_cselect_b64 s[8:9], -1, 0
	s_and_b64 s[0:1], s[0:1], s[8:9]
	s_andn2_b64 vcc, exec, s[0:1]
	v_readlane_b32 s0, v250, 58
	s_add_i32 s26, s0, 6
	s_cbranch_vccnz .LBB0_772
	s_waitcnt vmcnt(0)
	v_mov_b32_e32 v2, v202
	v_readlane_b32 s0, v251, 61
	v_readlane_b32 s38, v251, 58
	s_lshl_b32 s0, s0, 9
	s_lshl_b32 s38, s38, 7
	s_add_i32 s0, s0, s38
	s_add_i32 s38, s0, 0x80
	v_ashrrev_i32_e32 v0, 6, v2
	v_readlane_b32 s1, v250, 3
	v_add_u32_e32 v60, s0, v0
	s_mov_b32 s0, 0x8000
	v_cmp_gt_i32_e32 vcc, s0, v60
	s_and_saveexec_b64 s[42:43], vcc
	s_cbranch_execz .LBB0_704
	v_and_b32_e32 v3, 63, v2
	v_ashrrev_i32_e32 v36, 1, v60
	v_mov_b64_e32 v[4:5], s[24:25]
	v_bfe_u32 v35, v2, 6, 1
	s_add_u32 s98, s92, 0x800000
	s_addc_u32 s99, s93, 0
	s_add_u32 s100, s92, 0xa80000
	s_addc_u32 s101, s93, 0
	v_bfe_u32 v131, v202, 4, 2
	v_lshlrev_b32_e32 v131, 2, v131
	v_mad_i64_i32 v[4:5], s[0:1], v36, s96, v[4:5]
	v_lshlrev_b32_e32 v0, 5, v3
	v_lshl_add_u64 v[4:5], v[4:5], 0, v[0:1]
	v_lshlrev_b32_e32 v0, 11, v35
	v_cmp_eq_u32_e64 s[40:41], 0, v35
	v_lshl_add_u64 v[6:7], v[4:5], 0, v[0:1]
	v_mov_b32_e32 v51, v1
	v_cndmask_b32_e64 v0, v216, v217, s[40:41]
	v_lshlrev_b32_e32 v50, 1, v0
	v_lshl_add_u64 v[4:5], v[4:5], 0, v[50:51]
	global_load_dwordx4 v[30:33], v[6:7], off offset:16
	global_load_dwordx4 v[26:29], v[6:7], off
	global_load_dwordx4 v[22:25], v[4:5], off offset:16
	global_load_dwordx4 v[18:21], v[4:5], off
	v_lshlrev_b32_e32 v38, 4, v3
	v_and_b32_e32 v0, 64, v2
	v_bfe_u32 v34, v2, 4, 2
	v_cmp_ne_u32_e32 vcc, 0, v0
	v_lshlrev_b32_e32 v0, 2, v38
	s_and_saveexec_b64 s[0:1], vcc
	s_xor_b64 s[0:1], exec, s[0:1]
	s_cbranch_execz .LBB0_696
	v_readlane_b32 s8, v250, 33
	v_readlane_b32 s9, v250, 34
	s_nop 4
	global_load_dwordx4 v[2:5], v0, s[8:9] offset:48
	global_load_dwordx4 v[6:9], v0, s[8:9] offset:32
	global_load_dwordx4 v[10:13], v0, s[8:9] offset:16
	global_load_dwordx4 v[14:17], v0, s[8:9]

; DI unsigned xb_ld(unsigned* p)              { return __hip_atomic_load(p, __ATOMIC_RELAXED, __HIP_MEMORY_SCOPE_AGENT); }
; DI unsigned xb_add(unsigned* p, unsigned v) { return __hip_atomic_fetch_add(p, v, __ATOMIC_RELAXED, __HIP_MEMORY_SCOPE_AGENT); }
; #define XB_SPIN(cond, bar) do { unsigned _sp = 0; while (cond) { __builtin_amdgcn_s_sleep(1); \
;     if ((++_sp & 255u) == 0u) { if (xb_ld(&(bar)[XB_TMO])) break; if (_sp > XB_SPIN_CAP) { atomicAdd(&(bar)[XB_TMO], 1u); break; } } } } while (0)
; DI void phase_post(const Params& p, int l, int G, int bid) {
;     ...
;     for (int it = bid * 8 + wave; it < MSEG * 2; it += G * 8) {
;         const int lrow = it >> 1, grp = it & 1;
;         bf16_t* cp = P + (size_t)lrow * NPC + grp * 1024 + 16 * lane;
;         const u32x4 c0 = nc0, c1 = nc1, z0 = nz0, z1 = nz1, o0 = no0, o1 = no1;
;         const float inv = (grp == 0) ? 1.0f / ndn : 1.f;
;         if (it + G * 8 < MSEG * 2) PP_LOAD(it + G * 8);
; DI void xcd_barrier(const XcdBarrier& b) {
;     asm volatile("s_waitcnt vmcnt(0)" ::: "memory");
;     __syncthreads();
;     if (threadIdx.x == 0) {
;         unsigned* bar = b.bar;
;         __builtin_amdgcn_s_waitcnt(0);
;         unsigned nloc = b.st[0], nx = b.st[1];
;         if (nloc == 0u) { xcd_barrier_complete(bar, b.x, nloc, nx); b.st[0] = nloc; b.st[1] = nx; }
;         const unsigned old = xb_add(&bar[XB_XSUB(b.x)], 1u);
;         const unsigned gen = old / nloc;
;         if (old + 1u == (gen + 1u) * nloc) {
;             __builtin_amdgcn_fence(__ATOMIC_RELEASE, "agent");
;             asm volatile("s_waitcnt vmcnt(0)" ::: "memory");
;             const unsigned og = xb_add(&bar[XB_TOP], 1u);
;             const unsigned tg = og / nx;
;             if (og + 1u == (tg + 1u) * nx) xb_add(&bar[XB_TOPGEN], 1u);
;             else XB_SPIN(xb_ld(&bar[XB_TOPGEN]) == tg, bar);
;             __builtin_amdgcn_fence(__ATOMIC_ACQUIRE, "agent");
;             xb_add(&bar[XB_XGEN(b.x)], 1u);
;             asm volatile("s_waitcnt vmcnt(0)" ::: "memory");
;         } else {
;             XB_SPIN(xb_ld(&bar[XB_TOPGEN]) == gen, bar);
;             __builtin_amdgcn_fence(__ATOMIC_ACQUIRE, "agent");
;             asm volatile("s_waitcnt vmcnt(0)" ::: "memory");
;         }
;     }
;     __syncthreads();
.LBB0_701:
	v_add_u32_e32 v65, 8, v60
	s_mov_b32 s0, s38
	v_cmp_gt_i32_e32 vcc, s0, v65
	s_add_i32 s0, s38, -1
	v_cmp_lt_i32_e64 s[0:1], s0, v65
	s_or_b64 s[44:45], s[0:1], s[44:45]
	s_and_saveexec_b64 s[0:1], vcc
	s_cbranch_execz .LBB0_700
	v_ashrrev_i32_e32 v58, 1, v65
	v_mad_i64_i32 v[42:43], s[8:9], v58, s96, v[52:53]
	v_mov_b32_e32 v51, v1
	v_lshl_add_u64 v[38:39], v[42:43], 0, v[0:1]
	v_lshl_add_u64 v[46:47], v[42:43], 0, v[50:51]
	global_load_dwordx4 v[34:37], v[38:39], off offset:16
	s_nop 0
	global_load_dwordx4 v[38:41], v[38:39], off
	s_nop 0
	global_load_dwordx4 v[42:45], v[46:47], off offset:16
	s_nop 0
	global_load_dwordx4 v[46:49], v[46:47], off
	v_mov_b32_e32 v51, v66
	s_and_saveexec_b64 s[46:47], s[40:41]
	s_cbranch_execz .LBB0_699
	v_lshl_add_u32 v130, v58, 4, v131
	v_lshlrev_b32_e32 v129, 3, v130
	global_load_dwordx4 v[120:123], v129, s[98:99]
	global_load_dwordx4 v[124:127], v129, s[98:99] offset:16
	global_load_dword v128, v130, s[100:101]
	s_branch .LBB0_699
.LBB0_704:
	s_or_b64 exec, exec, s[42:43]
	s_cmp_ge_i32 s26, s33
	s_cbranch_scc1 .LBB0_772
	v_readlane_b32 s8, v252, 20
	v_readlane_b32 s9, v252, 21
	s_mov_b64 s[0:1], -1
	s_and_b64 vcc, exec, s[8:9]
	s_cbranch_vccz .LBB0_759
	v_readlane_b32 s17, v250, 60
	s_cmp_eq_u32 s17, 0
	s_cbranch_scc1 .Lppg2_slow
	s_waitcnt vmcnt(0)
	s_barrier
	s_mov_b64 s[0:1], exec
	v_readlane_b32 s8, v252, 2
	v_readlane_b32 s9, v252, 3
	s_and_b64 s[8:9], s[0:1], s[8:9]
	s_mov_b64 exec, s[8:9]
	s_cbranch_execz .Lppg2_join
	v_readlane_b32 s6, v251, 61
	v_readlane_b32 s42, v250, 61
	s_lshl_b32 s6, s6, 6
	s_add_i32 s6, s6, 0x6000
	s_add_u32 s40, s92, s6
	s_addc_u32 s41, s93, 0
	v_mov_b32_e32 v146, 0
	v_mov_b32_e32 v147, 1
	s_mov_b32 s43, 0
	s_nop 4
	global_atomic_add v146, v147, s[40:41]
.Lppg2_poll:
	global_load_dword v148, v146, s[40:41] sc1
	s_waitcnt vmcnt(0)
	v_readfirstlane_b32 s6, v148
	s_cmp_ge_u32 s6, s42
	s_cbranch_scc1 .Lppg2_done
	s_add_i32 s43, s43, 1
	s_sleep 1
	s_cmp_lt_u32 s43, 0x4000
	s_cbranch_scc1 .Lppg2_poll
.Lppg2_done:
	s_add_i32 s42, s42, 4
	s_nop 0
	v_writelane_b32 v250, s42, 61
	buffer_inv sc1
.Lppg2_join:
	s_or_b64 exec, exec, s[0:1]
	s_waitcnt vmcnt(0)
	s_barrier
	s_branch .LBB0_771
.Lppg2_slow:
	s_waitcnt vmcnt(0)
	s_barrier
	s_mov_b64 s[0:1], exec
	v_readlane_b32 s8, v252, 2
	v_readlane_b32 s9, v252, 3
	s_and_b64 s[8:9], s[0:1], s[8:9]
	s_mov_b64 exec, s[8:9]
	s_cbranch_execz .LBB0_758
	v_readlane_b32 s6, v250, 9
	s_waitcnt vmcnt(0) expcnt(0) lgkmcnt(0)
	s_nop 0
	v_mov_b32_e32 v0, s6
	ds_read_b32 v3, v0
	v_readlane_b32 s6, v250, 10
	s_waitcnt lgkmcnt(0)
	v_cmp_ne_u32_e32 vcc, 0, v3
	v_mov_b32_e32 v0, s6
	ds_read_b32 v2, v0
	s_cbranch_vccnz .LBB0_722
	s_mov_b32 s6, 1
	s_branch .LBB0_710
